# attention row-sum rewritten as scalar v_add_f32 tree in DA and MLA loops (on top of RS8 prologue, epilogue hoists, DA LDS pipelining)
# speedup vs baseline: 1.0014x; 1.0014x over previous
; DI float ex2(float x) { return __builtin_amdgcn_exp2f(x); }
; template <int MODE>
; DI void attn_unit(LAS unsigned char* lds, const bf16_t* Qg, int ldq, const bf16_t* Kg, int ldk, const bf16_t* VTg, int ldvt, bf16_t* Og, int ldo,
;                   int q0, int NT, const float* gout, const float* relb, float lam, float osc, const float* qgain) {
;     ...
;                 float rs = 0.f;
; #pragma unroll
;                 for (int i = 0; i < 16; ++i) { p0[i] = ex2(p0[i]); p1[i] = ex2(p1[i]); rs += p0[i] + p1[i]; }
;                 lrun += rs;
.LBB0_197:
	v_add_f32_e32 v241, v179, v196
	v_add_f32_e32 v242, v0, v178
	v_add_f32_e32 v243, v175, v177
	v_add_f32_e32 v244, v174, v176
	v_add_f32_e32 v245, v171, v173
	v_add_f32_e32 v206, v170, v172
	v_add_f32_e32 v207, v167, v169
	v_add_f32_e32 v210, v166, v168
	v_add_f32_e32 v211, v163, v165
	v_add_f32_e32 v230, v162, v164
	v_add_f32_e32 v231, v109, v195
	v_add_f32_e32 v233, v108, v110
	v_add_f32_e32 v234, v105, v107
	v_add_f32_e32 v236, v104, v106
	v_add_f32_e32 v237, v101, v103
	v_add_f32_e32 v238, v100, v102
	v_add_f32_e32 v241, v241, v242
	v_add_f32_e32 v243, v243, v244
	v_add_f32_e32 v245, v245, v206
	v_add_f32_e32 v207, v207, v210
	v_add_f32_e32 v211, v211, v230
	v_add_f32_e32 v231, v231, v233
	v_add_f32_e32 v234, v234, v236
	v_add_f32_e32 v237, v237, v238
	v_add_f32_e32 v241, v241, v243
	v_add_f32_e32 v245, v245, v207
	v_add_f32_e32 v211, v211, v231
	v_add_f32_e32 v234, v234, v237
	v_add_f32_e32 v241, v241, v245
	v_add_f32_e32 v211, v211, v234
	v_add_f32_e32 v241, v241, v211
	v_add_f32_e32 v153, v153, v241

; DI float ex2(float x) { return __builtin_amdgcn_exp2f(x); }
; template <int MODE>
; DI void attn_unit(LAS unsigned char* lds, const bf16_t* Qg, int ldq, const bf16_t* Kg, int ldk, const bf16_t* VTg, int ldvt, bf16_t* Og, int ldo,
;                   int q0, int NT, const float* gout, const float* relb, float lam, float osc, const float* qgain) {
;     ...
;                 float rs = 0.f;
; #pragma unroll
;                 for (int i = 0; i < 16; ++i) { p0[i] = ex2(p0[i]); p1[i] = ex2(p1[i]); rs += p0[i] + p1[i]; }
;                 lrun += rs;
.LBB0_245:
	v_add_f32_e32 v195, v159, v173
	v_add_f32_e32 v196, v158, v0
	v_add_f32_e32 v197, v155, v157
	v_add_f32_e32 v198, v154, v156
	v_add_f32_e32 v199, v151, v153
	v_add_f32_e32 v200, v150, v152
	v_add_f32_e32 v201, v145, v147
	v_add_f32_e32 v202, v144, v146
	v_add_f32_e32 v203, v87, v172
	v_add_f32_e32 v204, v86, v88
	v_add_f32_e32 v205, v83, v85
	v_add_f32_e32 v206, v82, v84
	v_add_f32_e32 v207, v81, v90
	v_add_f32_e32 v208, v76, v80
	v_add_f32_e32 v209, v73, v75
	v_add_f32_e32 v210, v72, v74
	v_add_f32_e32 v195, v195, v196
	v_add_f32_e32 v197, v197, v198
	v_add_f32_e32 v199, v199, v200
	v_add_f32_e32 v201, v201, v202
	v_add_f32_e32 v203, v203, v204
	v_add_f32_e32 v205, v205, v206
	v_add_f32_e32 v207, v207, v208
	v_add_f32_e32 v209, v209, v210
	v_add_f32_e32 v195, v195, v197
	v_add_f32_e32 v199, v199, v201
	v_add_f32_e32 v203, v203, v205
	v_add_f32_e32 v207, v207, v209
	v_add_f32_e32 v195, v195, v199
	v_add_f32_e32 v203, v203, v207
	v_add_f32_e32 v195, v195, v203
	v_add_f32_e32 v133, v133, v195
